# v1_hoist
# baseline (speedup 1.0000x reference)
; #define STAGE(PP, RSRC, br, kt) do { const int _so = ((br) * K + (kt) * BK) * 2; \
;       __builtin_amdgcn_raw_ptr_buffer_load_lds(RSRC, LDSP((char*)(PP) + ldsoff), 16, voff0, _so, 0, 0); \
;       __builtin_amdgcn_raw_ptr_buffer_load_lds(RSRC, LDSP((char*)(PP) + ldsoff + 8192), 16, voff1, _so, 0, 0); \
;     } while (0)
; #define BAR __builtin_amdgcn_s_barrier()
; __device__ __forceinline__ void gemm_tile(const Params& P, const GArgs& ga, const TileDesc& td, int wid_s) {
;     ...
;   STAGE(SB(0, 0), Bt, bcol, 0); STAGE(SA(0, 0), A, brow, 0);
;   STAGE(SB(0, 1), Bt, bcol + HALF, 0); STAGE(SA(0, 1), A, brow + HALF, 0);
;   if (wr == 1) BAR;
; __device__ __forceinline__ void gemm_phase(const Params& P, const GArgs& ga, int wid_s, int first, int stride) {
;     ...
;   for (int t = first; t < nitems; t += stride) {
;     const TileDesc td = get_tile(ga, t, nwg, nM, nN, nkt_all);
;     gemm_tile(P, ga, td, wid_s);
;     __syncthreads();
.LBB0_290:
	s_add_i32 s59, s59, s39
	s_cmp_lt_i32 s59, s91
	s_cbranch_scc1 .Lnt_back
	s_waitcnt vmcnt(0)
	s_barrier
	s_branch .LBB0_260
.Lnt_back:
	s_barrier
	v_readlane_b32 s0, v235, 0
	v_readlane_b32 s1, v235, 1
	v_readlane_b32 s4, v235, 2
	v_readlane_b32 s5, v235, 3
	v_readlane_b32 s6, v235, 4
	v_readlane_b32 s7, v235, 5
	v_readlane_b32 s8, v235, 6
	v_readlane_b32 s9, v235, 7
	v_readlane_b32 s15, v235, 8
	v_readlane_b32 s17, v235, 9
	v_readlane_b32 s38, v235, 10
	v_readlane_b32 s50, v235, 11
	v_readlane_b32 s51, v235, 12
	v_readlane_b32 s79, v235, 13
	v_readlane_b32 s84, v235, 14
	v_readlane_b32 s85, v235, 15
	v_readlane_b32 s86, v235, 16
	v_readlane_b32 s87, v235, 17
	v_readlane_b32 s92, v235, 18
	v_readlane_b32 s98, v235, 19
	v_readlane_b32 s99, v235, 20
	v_mov_b32_e32 v0, v200
	v_mov_b32_e32 v148, v232
	v_mov_b32_e32 v149, v233
	v_ashrrev_i32_e32 v24, 8, v0
	s_nop 1
	v_cmp_eq_u32_e32 vcc, 1, v24
	s_nop 4
	s_branch .Lnt_entry

; #define WAIT_V(n) asm volatile("s_waitcnt vmcnt(" #n ")" ::: "memory")
; #define BAR __builtin_amdgcn_s_barrier()
; __device__ __forceinline__ void gemm_tile(const Params& P, const GArgs& ga, const TileDesc& td, int wid_s) {
;     ...
;   if (wr == 1) BAR;
;   WAIT_V(4); BAR;
.Lnt_entry:
	s_and_saveexec_b64 s[0:1], vcc
	s_cbranch_execz .LBB0_304
	s_barrier

; __device__ __forceinline__ TileDesc get_tile(const GArgs& ga, int t, int nwg, int nM, int nN, int nkt_all) {
;   TileDesc td; td.kt0 = 0; td.nkt = nkt_all; td.mode = ga.mode; td.sp = 0;
;   int pm, pn;
;   if (t < nwg) {
;     tile_coords(t, nM, nN, pm, pn);
;   } else {
;     const int j = t - nwg; td.sp = j & 7; const int tt = j >> 3;
;     pm = NP / BM + tt / nN; pn = tt % nN;
;     if (nkt_all == 88) { td.kt0 = td.sp < 4 ? td.sp * 12 : 48 + (td.sp - 4) * 10; td.nkt = td.sp < 4 ? 12 : 10; }
;     else { td.nkt = nkt_all >> 3; td.kt0 = td.sp * td.nkt; }
;     td.mode = M_PART;
;   }
; __device__ __forceinline__ void gemm_phase(const Params& P, const GArgs& ga, int wid_s, int first, int stride) {
;     ...
;   for (int t = first; t < nitems; t += stride) {
;     const TileDesc td = get_tile(ga, t, nwg, nM, nN, nkt_all);
.LBB0_313:
	s_or_b64 exec, exec, s[0:1]
	s_add_i32 s0, s59, s39
	s_cmp_lt_i32 s0, s91
	s_cbranch_scc0 .Lnt_skip
	v_writelane_b32 v234, s0, 0
	v_writelane_b32 v234, s1, 1
	v_writelane_b32 v234, s4, 2
	v_writelane_b32 v234, s5, 3
	v_writelane_b32 v234, s6, 4
	v_writelane_b32 v234, s7, 5
	v_writelane_b32 v234, s8, 6
	v_writelane_b32 v234, s9, 7
	v_writelane_b32 v234, s15, 8
	v_writelane_b32 v234, s17, 9
	v_writelane_b32 v234, s38, 10
	v_writelane_b32 v234, s50, 11
	v_writelane_b32 v234, s51, 12
	v_writelane_b32 v234, s79, 13
	v_writelane_b32 v234, s84, 14
	v_writelane_b32 v234, s85, 15
	v_writelane_b32 v234, s86, 16
	v_writelane_b32 v234, s87, 17
	v_writelane_b32 v234, s92, 18
	v_writelane_b32 v234, s98, 19
	v_writelane_b32 v234, s99, 20
	s_add_i32 s59, s59, s39
	s_cmp_ge_i32 s59, s54
	s_mov_b64 s[0:1], -1
	s_cbranch_scc0 .Lnt_300
	s_sub_i32 s0, s59, s54
	s_lshr_b32 s5, s0, 3
	s_mul_hi_u32 s0, s5, s45
	s_mul_i32 s1, s0, s78
	s_sub_i32 s1, s5, s1
	s_and_b32 s87, s59, 7
	s_add_i32 s4, s0, 1
	s_sub_i32 s6, s1, s78
	s_cmp_ge_u32 s1, s78
	s_cselect_b32 s0, s4, s0
	s_cselect_b32 s1, s6, s1
	s_add_i32 s4, s0, 1
	s_cmp_ge_u32 s1, s78
	s_cselect_b32 s6, s4, s0
	s_mov_b64 s[0:1], -1
	s_and_b64 vcc, exec, s[34:35]
	s_cbranch_vccz .Lnt_294
	s_mul_i32 s4, s87, s42
	s_mov_b64 s[0:1], 0

; #define STAGE(PP, RSRC, br, kt) do { const int _so = ((br) * K + (kt) * BK) * 2; \
;       __builtin_amdgcn_raw_ptr_buffer_load_lds(RSRC, LDSP((char*)(PP) + ldsoff), 16, voff0, _so, 0, 0); \
;       __builtin_amdgcn_raw_ptr_buffer_load_lds(RSRC, LDSP((char*)(PP) + ldsoff + 8192), 16, voff1, _so, 0, 0); \
;     } while (0)
; __device__ __forceinline__ void gemm_tile(const Params& P, const GArgs& ga, const TileDesc& td, int wid_s) {
;     ...
;   { int _r, _c; stage_rc(tid_ * 16, _r, _c); voff0 = (_r * K + _c) * 2;
;     stage_rc(tid_ * 16 + 8192, _r, _c); voff1 = (_r * K + _c) * 2; }
;   const int ldsoff = wid_s * 1024;
;   f32x4 acc[2][2][4][2] = {};
;   bf16x8 At[4][2], B0[2][2], B1[2][2];
;   const int nt = nkt;
;   STAGE(SB(0, 0), Bt, bcol, 0); STAGE(SA(0, 0), A, brow, 0);
;   STAGE(SB(0, 1), Bt, bcol + HALF, 0); STAGE(SA(0, 1), A, brow + HALF, 0);
.Lnt_300:
	s_mov_b64 s[50:51], s[98:99]
	s_andn2_b64 vcc, exec, s[0:1]
	s_mov_b32 s79, 5
	s_cbranch_vccnz .Lnt_302
	s_ashr_i32 s0, s59, 31
	s_lshr_b32 s0, s0, 29
	s_add_i32 s0, s59, s0
	s_ashr_i32 s1, s0, 3
	s_and_b32 s0, s0, -8
	s_sub_i32 s0, s59, s0
	s_lshr_b32 s4, s0, 31
	s_or_b32 s4, s43, s4
	s_mul_i32 s0, s4, s0
	s_add_i32 s0, s0, s1
	s_abs_i32 s4, s0
	s_mul_hi_u32 s5, s4, s46
	s_mul_i32 s6, s5, s44
	s_sub_i32 s4, s4, s6
	s_ashr_i32 s1, s0, 31
	s_add_i32 s6, s5, 1
	s_sub_i32 s7, s4, s44
	s_cmp_ge_u32 s4, s44
	s_cselect_b32 s5, s6, s5
	s_cselect_b32 s4, s7, s4
	s_add_i32 s6, s5, 1
	s_cmp_ge_u32 s4, s44
	s_cselect_b32 s4, s6, s5
	s_xor_b32 s4, s4, s1
	s_sub_i32 s1, s4, s1
	s_lshl_b32 s5, s1, 2
	s_sub_i32 s4, s41, s5
	s_min_i32 s6, s4, 4
	s_abs_i32 s7, s6
	v_cvt_f32_u32_e32 v236, s7
	s_sub_i32 s9, 0, s7
	s_mul_i32 s1, s1, s44
	s_sub_i32 s0, s0, s1
	v_rcp_iflag_f32_e32 v236, v236
	s_abs_i32 s8, s0
	s_xor_b32 s1, s0, s6
	s_ashr_i32 s1, s1, 31
	v_mul_f32_e32 v236, 0x4f7ffffe, v236
	v_cvt_u32_f32_e32 v236, v236
	s_mov_b32 s4, 0
	s_mov_b32 s79, s53
	s_mov_b32 s87, 0
	v_readfirstlane_b32 s15, v236
	s_mul_i32 s9, s9, s15
	s_mul_hi_u32 s9, s15, s9
	s_add_i32 s15, s15, s9
	s_mul_hi_u32 s9, s8, s15
	s_mul_i32 s15, s9, s7
	s_sub_i32 s8, s8, s15
	s_add_i32 s15, s9, 1
	s_sub_i32 s17, s8, s7
	s_cmp_ge_u32 s8, s7
	s_cselect_b32 s9, s15, s9
	s_cselect_b32 s8, s17, s8
	s_add_i32 s15, s9, 1
	s_cmp_ge_u32 s8, s7
	s_cselect_b32 s7, s15, s9
	s_xor_b32 s7, s7, s1
	s_sub_i32 s15, s7, s1
	s_mul_i32 s1, s15, s6
	s_sub_i32 s0, s0, s1
	s_add_i32 s86, s0, s5
	s_mov_b32 s17, s76
.Lnt_302:
	v_mov_b32_e32 v236, v200
	s_lshl_b32 s84, s86, 8
	v_bfe_i32 v239, v236, 27, 1
	v_lshlrev_b32_e32 v237, 4, v236
	v_lshrrev_b32_e32 v239, 22, v239
	v_add_u32_e32 v239, v237, v239
	v_and_b32_e32 v239, 0xfffffc00, v239
	v_ashrrev_i32_e32 v238, 31, v236
	v_sub_u32_e32 v239, v237, v239
	v_lshrrev_b32_e32 v238, 26, v238
	v_lshrrev_b32_e32 v240, 4, v239
	v_add_u32_e32 v238, v236, v238
	v_bitop3_b32 v240, v240, v239, 32 bitop3:0x6c
	v_ashrrev_i32_e32 v239, 31, v239
	v_ashrrev_i32_e32 v238, 6, v238
	v_lshrrev_b32_e32 v239, 26, v239
	v_lshlrev_b32_e32 v241, 3, v238
	v_add_u32_e32 v239, v240, v239
	v_and_b32_e32 v241, 0x7ffffff0, v241
	v_ashrrev_i32_e32 v239, 6, v239
	v_add_u32_e32 v241, v239, v241
	v_mul_i32_i24_e32 v239, 64, v239
	v_sub_u32_e32 v239, v240, v239
	v_lshlrev_b32_e32 v238, 5, v238
	v_ashrrev_i16_sdwa v239, v201, sext(v239) dst_sel:DWORD dst_unused:UNUSED_PAD src0_sel:DWORD src1_sel:BYTE_0
	v_mul_lo_u32 v240, v241, s93
	v_bfe_i32 v239, v239, 0, 16
	v_and_or_b32 v238, v238, 32, v240
	v_add_u32_e32 v237, 0x2000, v237
	v_add_lshl_u32 v232, v238, v239, 1
	v_ashrrev_i32_e32 v238, 31, v237
	v_lshrrev_b32_e32 v238, 22, v238
	v_add_u32_e32 v238, v237, v238
	v_ashrrev_i32_e32 v238, 10, v238
	v_mul_i32_i24_e32 v239, 0x400, v238
	v_sub_u32_e32 v237, v237, v239
	v_lshrrev_b32_e32 v239, 4, v237
	s_lshl_b32 s92, s15, 8
	s_lshl_b32 s0, s4, 7
	v_bitop3_b32 v237, v239, v237, 32 bitop3:0x6c
	s_add_u32 s8, s60, s0
	v_ashrrev_i32_e32 v240, 31, v237
	s_addc_u32 s1, s61, 0
	v_lshrrev_b32_e32 v240, 26, v240
	s_and_b32 s9, s1, 0xffff
	v_lshlrev_b32_e32 v239, 3, v238
	v_add_u32_e32 v240, v237, v240
	s_add_u32 s4, s64, s0
	v_and_b32_e32 v239, 0x7ffffff0, v239
	v_ashrrev_i32_e32 v241, 6, v240
	v_and_b32_e32 v240, 0xc0, v240
	s_addc_u32 s0, s65, 0
	v_add_u32_e32 v239, v241, v239
	v_sub_u32_e32 v237, v237, v240
	s_and_b32 s5, s0, 0xffff
	v_lshlrev_b32_e32 v238, 5, v238
	v_ashrrev_i16_sdwa v237, v201, sext(v237) dst_sel:DWORD dst_unused:UNUSED_PAD src0_sel:DWORD src1_sel:BYTE_0
	v_mul_lo_u32 v239, v239, s93
	s_mul_i32 s0, s92, s93
	s_mov_b32 m0, s88
	s_mov_b32 s6, s10
	s_mov_b32 s7, s11
	v_bfe_i32 v237, v237, 0, 16
	v_and_or_b32 v238, v238, 32, v239
	s_lshl_b32 s99, s0, 1
	v_add_lshl_u32 v233, v238, v237, 1
	buffer_load_dwordx4 v232, s[4:7], s99 offen lds
	s_mov_b32 m0, s89
	s_mul_i32 s1, s84, s93
	buffer_load_dwordx4 v233, s[4:7], s99 offen lds
	s_lshl_b32 s98, s1, 1
	s_mov_b32 m0, s52
	s_add_i32 s0, s0, s47
	buffer_load_dwordx4 v232, s[8:11], s98 offen lds
	s_mov_b32 m0, s94
	s_lshl_b32 s38, s0, 1
	buffer_load_dwordx4 v233, s[8:11], s98 offen lds
	s_mov_b32 m0, s95
	s_add_i32 s1, s1, s47
	buffer_load_dwordx4 v232, s[4:7], s38 offen lds
	s_mov_b32 m0, s3
	s_lshl_b32 s85, s1, 1
	buffer_load_dwordx4 v233, s[4:7], s38 offen lds
	s_mov_b32 m0, s57
	s_nop 0
	s_nop 0
	buffer_load_dwordx4 v232, s[8:11], s85 offen lds
	s_mov_b32 m0, s56
	s_nop 0
	buffer_load_dwordx4 v233, s[8:11], s85 offen lds
	s_sub_i32 s59, s59, s39
	v_writelane_b32 v235, s0, 0
	v_writelane_b32 v235, s1, 1
	v_writelane_b32 v235, s4, 2
	v_writelane_b32 v235, s5, 3
	v_writelane_b32 v235, s6, 4
	v_writelane_b32 v235, s7, 5
	v_writelane_b32 v235, s8, 6
	v_writelane_b32 v235, s9, 7
	v_writelane_b32 v235, s15, 8
	v_writelane_b32 v235, s17, 9
	v_writelane_b32 v235, s38, 10
	v_writelane_b32 v235, s50, 11
	v_writelane_b32 v235, s51, 12
	v_writelane_b32 v235, s79, 13
	v_writelane_b32 v235, s84, 14
	v_writelane_b32 v235, s85, 15
	v_writelane_b32 v235, s86, 16
	v_writelane_b32 v235, s87, 17
	v_writelane_b32 v235, s92, 18
	v_writelane_b32 v235, s98, 19
	v_writelane_b32 v235, s99, 20
	s_nop 1
	v_readlane_b32 s0, v234, 0
	v_readlane_b32 s1, v234, 1
	v_readlane_b32 s4, v234, 2
	v_readlane_b32 s5, v234, 3
	v_readlane_b32 s6, v234, 4
	v_readlane_b32 s7, v234, 5
	v_readlane_b32 s8, v234, 6
	v_readlane_b32 s9, v234, 7
	v_readlane_b32 s15, v234, 8
	v_readlane_b32 s17, v234, 9
	v_readlane_b32 s38, v234, 10
	v_readlane_b32 s50, v234, 11
	v_readlane_b32 s51, v234, 12
	v_readlane_b32 s79, v234, 13
	v_readlane_b32 s84, v234, 14
	v_readlane_b32 s85, v234, 15
	v_readlane_b32 s86, v234, 16
	v_readlane_b32 s87, v234, 17
	v_readlane_b32 s92, v234, 18
	v_readlane_b32 s98, v234, 19
	v_readlane_b32 s99, v234, 20
	s_nop 4
; __device__ __forceinline__ float eps_s() { float e = 1e-6f; asm volatile("" : "+s"(e)); return e; }
; __device__ __forceinline__ void gemm_tile(const Params& P, const GArgs& ga, const TileDesc& td, int wid_s) {
;     ...
;   const float EPSN = eps_s();
;   const int tid2_ = ltid(wid_s);
;   const int ewr = tid2_ >> 8, ewc = (tid2_ >> 6) & 3, efr = tid2_ & 15, efq = (tid2_ >> 4) & 3;
;   const int rbase = brow + ewr * 64 + efq * 4;
;   const int x4 = (ewc * 16 + efr) * 4;
;   const int c4 = bcol + x4;
;     ...
;   } else if (mode == M_PART) {
;     u16* __restrict__ pp = WSU(PART) + ((size_t)sp * NS + (rbase - NP)) * DM + c4;
;     static_for<32>([&](auto ic) __attribute__((always_inline)) {
;       EPI_IDX;
;       uint2 o; o.x = pack2(acc[ai][0][m][0][j], acc[ai][0][m][1][j]); o.y = pack2(acc[ai][1][m][0][j], acc[ai][1][m][1][j]);
;       *reinterpret_cast<uint2*>(pp + (size_t)rl * DM) = o;
;       if constexpr ((idx & 7) == 7) __builtin_amdgcn_sched_barrier(0);
;     });
.Lnt_skip:
	s_mov_b32 s17, 0x358637bd
	v_mov_b32_e32 v0, v200
	s_mov_b64 s[0:1], -1
	v_ashrrev_i32_e32 v130, 2, v0
	v_and_b32_e32 v203, 15, v0
	v_and_b32_e32 v130, 0xffffffc0, v130
	v_lshrrev_b32_e32 v131, 2, v0
	v_and_b32_e32 v0, 0xc0, v0
	v_add_u32_e32 v130, s84, v130
	v_lshl_or_b32 v0, v203, 2, v0
	v_and_or_b32 v166, v131, 12, v130
	v_or_b32_e32 v168, s92, v0
	s_mov_b64 s[84:85], 0
	s_cmp_lt_i32 s79, 2
	s_mov_b64 s[8:9], 0
	s_cbranch_scc1 .LBB0_597
	s_cmp_gt_i32 s79, 2
	s_cbranch_scc0 .LBB0_323
	s_cmp_gt_i32 s79, 4
	s_cbranch_scc0 .LBB0_319
	s_cmp_eq_u32 s79, 5
	s_mov_b64 s[8:9], -1
	s_cbranch_scc0 .LBB0_318
	s_lshl_b32 s0, s87, 22
	v_readlane_b32 s4, v231, 62
	v_ashrrev_i32_e32 v167, 31, v166
	v_readlane_b32 s5, v231, 63
	s_add_u32 s0, s4, s0
	v_lshlrev_b64 v[130:131], 12, v[166:167]
	s_addc_u32 s1, s5, 0
	v_lshl_add_u64 v[130:131], s[0:1], 0, v[130:131]
	v_ashrrev_i32_e32 v169, 31, v168
	v_lshl_add_u64 v[130:131], v[168:169], 1, v[130:131]
	s_mov_b32 s0, 0xfc001000
	v_add_co_u32_e32 v134, vcc, s0, v130
	v_cvt_pk_bf16_f32 v132, v114, v118
	v_cvt_pk_bf16_f32 v133, v126, v122
	v_addc_co_u32_e32 v135, vcc, -1, v131, vcc
	global_store_dwordx2 v[134:135], v[132:133], off offset:-4096
	v_cvt_pk_bf16_f32 v132, v115, v119
	v_cvt_pk_bf16_f32 v133, v127, v123
	s_mov_b32 s0, 0xfc003000
	global_store_dwordx2 v[134:135], v[132:133], off
	v_add_co_u32_e32 v134, vcc, s0, v130
	v_cvt_pk_bf16_f32 v132, v116, v120
	v_cvt_pk_bf16_f32 v133, v128, v124
	v_addc_co_u32_e32 v135, vcc, -1, v131, vcc
	global_store_dwordx2 v[134:135], v[132:133], off offset:-4096
	v_cvt_pk_bf16_f32 v132, v117, v121
	v_cvt_pk_bf16_f32 v133, v129, v125
	s_mov_b32 s0, 0xfc011000
	global_store_dwordx2 v[134:135], v[132:133], off
	v_add_co_u32_e32 v134, vcc, s0, v130
	v_cvt_pk_bf16_f32 v132, v98, v102
	v_cvt_pk_bf16_f32 v133, v110, v106
	v_addc_co_u32_e32 v135, vcc, -1, v131, vcc
	global_store_dwordx2 v[134:135], v[132:133], off offset:-4096
	v_cvt_pk_bf16_f32 v132, v99, v103
	v_cvt_pk_bf16_f32 v133, v111, v107
	s_mov_b32 s0, 0xfc013000
	global_store_dwordx2 v[134:135], v[132:133], off
	v_add_co_u32_e32 v134, vcc, s0, v130
	v_cvt_pk_bf16_f32 v132, v100, v104
	v_cvt_pk_bf16_f32 v133, v112, v108
	v_addc_co_u32_e32 v135, vcc, -1, v131, vcc
	global_store_dwordx2 v[134:135], v[132:133], off offset:-4096
	v_cvt_pk_bf16_f32 v132, v101, v105
	v_cvt_pk_bf16_f32 v133, v113, v109
	global_store_dwordx2 v[134:135], v[132:133], off
	s_mov_b32 s0, 0xfc021000
	v_add_co_u32_e32 v134, vcc, s0, v130
	v_cvt_pk_bf16_f32 v132, v82, v86
	v_cvt_pk_bf16_f32 v133, v94, v90
	v_addc_co_u32_e32 v135, vcc, -1, v131, vcc
	global_store_dwordx2 v[134:135], v[132:133], off offset:-4096
	v_cvt_pk_bf16_f32 v132, v83, v87
	v_cvt_pk_bf16_f32 v133, v95, v91
	s_mov_b32 s0, 0xfc023000
	global_store_dwordx2 v[134:135], v[132:133], off
	v_add_co_u32_e32 v134, vcc, s0, v130
	v_cvt_pk_bf16_f32 v132, v84, v88
	v_cvt_pk_bf16_f32 v133, v96, v92
	v_addc_co_u32_e32 v135, vcc, -1, v131, vcc
	global_store_dwordx2 v[134:135], v[132:133], off offset:-4096
	v_cvt_pk_bf16_f32 v132, v85, v89
	v_cvt_pk_bf16_f32 v133, v97, v93
	s_mov_b32 s0, 0xfc031000
	global_store_dwordx2 v[134:135], v[132:133], off
	v_add_co_u32_e32 v134, vcc, s0, v130
	v_cvt_pk_bf16_f32 v132, v66, v70
	v_cvt_pk_bf16_f32 v133, v78, v74
	v_addc_co_u32_e32 v135, vcc, -1, v131, vcc
	global_store_dwordx2 v[134:135], v[132:133], off offset:-4096
	v_cvt_pk_bf16_f32 v132, v67, v71
	v_cvt_pk_bf16_f32 v133, v79, v75
	s_mov_b32 s0, 0xfc033000
	global_store_dwordx2 v[134:135], v[132:133], off
	v_add_co_u32_e32 v134, vcc, s0, v130
	v_cvt_pk_bf16_f32 v132, v68, v72
	v_cvt_pk_bf16_f32 v133, v80, v76
	v_addc_co_u32_e32 v135, vcc, -1, v131, vcc
	global_store_dwordx2 v[134:135], v[132:133], off offset:-4096
	v_cvt_pk_bf16_f32 v132, v69, v73
	v_cvt_pk_bf16_f32 v133, v81, v77
	global_store_dwordx2 v[134:135], v[132:133], off
	s_mov_b32 s0, 0xfc081000
	v_add_co_u32_e32 v134, vcc, s0, v130
	v_cvt_pk_bf16_f32 v132, v50, v54
	v_cvt_pk_bf16_f32 v133, v62, v58
	v_addc_co_u32_e32 v135, vcc, -1, v131, vcc
	global_store_dwordx2 v[134:135], v[132:133], off offset:-4096
	v_cvt_pk_bf16_f32 v132, v51, v55
	v_cvt_pk_bf16_f32 v133, v63, v59
	s_mov_b32 s0, 0xfc083000
	global_store_dwordx2 v[134:135], v[132:133], off
	v_add_co_u32_e32 v134, vcc, s0, v130
	v_cvt_pk_bf16_f32 v132, v52, v56
	v_cvt_pk_bf16_f32 v133, v64, v60
	v_addc_co_u32_e32 v135, vcc, -1, v131, vcc
	global_store_dwordx2 v[134:135], v[132:133], off offset:-4096
	v_cvt_pk_bf16_f32 v132, v53, v57
	v_cvt_pk_bf16_f32 v133, v65, v61
	s_mov_b32 s0, 0xfc091000
	global_store_dwordx2 v[134:135], v[132:133], off
	v_add_co_u32_e32 v134, vcc, s0, v130
	v_cvt_pk_bf16_f32 v132, v34, v38
	v_cvt_pk_bf16_f32 v133, v46, v42
	v_addc_co_u32_e32 v135, vcc, -1, v131, vcc
	global_store_dwordx2 v[134:135], v[132:133], off offset:-4096
	v_cvt_pk_bf16_f32 v132, v35, v39
	v_cvt_pk_bf16_f32 v133, v47, v43
	s_mov_b32 s0, 0xfc093000
	global_store_dwordx2 v[134:135], v[132:133], off
	v_add_co_u32_e32 v134, vcc, s0, v130
	v_cvt_pk_bf16_f32 v132, v36, v40
	v_cvt_pk_bf16_f32 v133, v48, v44
	v_addc_co_u32_e32 v135, vcc, -1, v131, vcc
	global_store_dwordx2 v[134:135], v[132:133], off offset:-4096
	v_cvt_pk_bf16_f32 v132, v37, v41
	v_cvt_pk_bf16_f32 v133, v49, v45
	global_store_dwordx2 v[134:135], v[132:133], off
	s_mov_b32 s0, 0xfc0a1000
	v_add_co_u32_e32 v134, vcc, s0, v130
	v_cvt_pk_bf16_f32 v132, v18, v22
	v_cvt_pk_bf16_f32 v133, v30, v26
	v_addc_co_u32_e32 v135, vcc, -1, v131, vcc
	global_store_dwordx2 v[134:135], v[132:133], off offset:-4096
	v_cvt_pk_bf16_f32 v132, v19, v23
	v_cvt_pk_bf16_f32 v133, v31, v27
	s_mov_b32 s0, 0xfc0a3000
	global_store_dwordx2 v[134:135], v[132:133], off
	v_add_co_u32_e32 v134, vcc, s0, v130
	v_cvt_pk_bf16_f32 v132, v20, v24
	v_cvt_pk_bf16_f32 v133, v32, v28
	v_addc_co_u32_e32 v135, vcc, -1, v131, vcc
	global_store_dwordx2 v[134:135], v[132:133], off offset:-4096
	v_cvt_pk_bf16_f32 v132, v21, v25
	v_cvt_pk_bf16_f32 v133, v33, v29
	s_mov_b32 s0, 0xfc0b1000
	global_store_dwordx2 v[134:135], v[132:133], off
	v_add_co_u32_e32 v134, vcc, s0, v130
	v_cvt_pk_bf16_f32 v132, v2, v6
	v_cvt_pk_bf16_f32 v133, v14, v10
	v_addc_co_u32_e32 v135, vcc, -1, v131, vcc
	global_store_dwordx2 v[134:135], v[132:133], off offset:-4096
	v_cvt_pk_bf16_f32 v132, v3, v7
	v_cvt_pk_bf16_f32 v133, v15, v11
	s_mov_b32 s0, 0xfc0b2000
	global_store_dwordx2 v[134:135], v[132:133], off
	v_add_co_u32_e32 v134, vcc, s0, v130
	v_cvt_pk_bf16_f32 v132, v4, v8
	s_nop 0
	v_addc_co_u32_e32 v135, vcc, -1, v131, vcc
	v_cvt_pk_bf16_f32 v133, v16, v12
	v_add_co_u32_e32 v130, vcc, 0xfc0b3000, v130
	global_store_dwordx2 v[134:135], v[132:133], off
	v_cvt_pk_bf16_f32 v132, v5, v9
	v_cvt_pk_bf16_f32 v133, v17, v13
	v_addc_co_u32_e32 v131, vcc, -1, v131, vcc
	global_store_dwordx2 v[130:131], v[132:133], off
	s_mov_b64 s[8:9], 0

; __global__ void __launch_bounds__(512, 2) mega(Params P) {
	.amdhsa_kernel _Z4mega6Params
		.amdhsa_group_segment_fixed_size 0
		.amdhsa_private_segment_fixed_size 0
		.amdhsa_kernarg_size 464
		.amdhsa_user_sgpr_count 2
		.amdhsa_user_sgpr_dispatch_ptr 0
		.amdhsa_user_sgpr_queue_ptr 0
		.amdhsa_user_sgpr_kernarg_segment_ptr 1
		.amdhsa_user_sgpr_dispatch_id 0
		.amdhsa_user_sgpr_kernarg_preload_length 0
		.amdhsa_user_sgpr_kernarg_preload_offset 0
		.amdhsa_user_sgpr_private_segment_size 0
		.amdhsa_uses_dynamic_stack 0
		.amdhsa_enable_private_segment 0
		.amdhsa_system_sgpr_workgroup_id_x 1
		.amdhsa_system_sgpr_workgroup_id_y 0
		.amdhsa_system_sgpr_workgroup_id_z 0
		.amdhsa_system_sgpr_workgroup_info 0
		.amdhsa_system_vgpr_workitem_id 2
		.amdhsa_next_free_vgpr 248
		.amdhsa_next_free_sgpr 100
		.amdhsa_accum_offset 248
		.amdhsa_reserve_vcc 1
		.amdhsa_float_round_mode_32 0
		.amdhsa_float_round_mode_16_64 0
		.amdhsa_float_denorm_mode_32 3
		.amdhsa_float_denorm_mode_16_64 3
		.amdhsa_dx10_clamp 1
		.amdhsa_ieee_mode 1
		.amdhsa_fp16_overflow 0
		.amdhsa_tg_split 0
		.amdhsa_exception_fp_ieee_invalid_op 0
		.amdhsa_exception_fp_denorm_src 0
		.amdhsa_exception_fp_ieee_div_zero 0
		.amdhsa_exception_fp_ieee_overflow 0
		.amdhsa_exception_fp_ieee_underflow 0
		.amdhsa_exception_fp_ieee_inexact 0
		.amdhsa_exception_int_div_zero 0
	.end_amdhsa_kernel

; __global__ void __launch_bounds__(512, 2) mega(Params P) {
amdhsa.kernels:
  - .agpr_count:     0
    .args:
      - .offset:         0
        .size:           208
        .value_kind:     by_value
      - .offset:         208
        .size:           4
        .value_kind:     hidden_block_count_x
      - .offset:         212
        .size:           4
        .value_kind:     hidden_block_count_y
      - .offset:         216
        .size:           4
        .value_kind:     hidden_block_count_z
      - .offset:         220
        .size:           2
        .value_kind:     hidden_group_size_x
      - .offset:         222
        .size:           2
        .value_kind:     hidden_group_size_y
      - .offset:         224
        .size:           2
        .value_kind:     hidden_group_size_z
      - .offset:         226
        .size:           2
        .value_kind:     hidden_remainder_x
      - .offset:         228
        .size:           2
        .value_kind:     hidden_remainder_y
      - .offset:         230
        .size:           2
        .value_kind:     hidden_remainder_z
      - .offset:         248
        .size:           8
        .value_kind:     hidden_global_offset_x
      - .offset:         256
        .size:           8
        .value_kind:     hidden_global_offset_y
      - .offset:         264
        .size:           8
        .value_kind:     hidden_global_offset_z
      - .offset:         272
        .size:           2
        .value_kind:     hidden_grid_dims
      - .offset:         296
        .size:           8
        .value_kind:     hidden_multigrid_sync_arg
      - .offset:         328
        .size:           4
        .value_kind:     hidden_dynamic_lds_size
    .group_segment_fixed_size: 0
    .kernarg_segment_align: 8
    .kernarg_segment_size: 464
    .language:       OpenCL C
    .language_version:
      - 2
      - 0
    .max_flat_workgroup_size: 512
    .name:           _Z4mega6Params
    .private_segment_fixed_size: 0
    .sgpr_count:     106
    .sgpr_spill_count: 137
    .symbol:         _Z4mega6Params.kd
    .uniform_work_group_size: 1
    .uses_dynamic_stack: false
    .vgpr_count:     248
    .vgpr_spill_count: 0
    .wavefront_size: 64
